# sgu_mix work queue moved from P3a (after selection) to the tail of P3b (after the NSA queue), on top of v9
# baseline (speedup 1.0000x reference)
; __device__ __forceinline__ unsigned xb_ld(unsigned* p)              { return __hip_atomic_load(p, __ATOMIC_RELAXED, __HIP_MEMORY_SCOPE_AGENT); }
; __device__ __forceinline__ unsigned xb_add(unsigned* p, unsigned v) { return __hip_atomic_fetch_add(p, v, __ATOMIC_RELAXED, __HIP_MEMORY_SCOPE_AGENT); }
; #define XB_SPIN(cond, bar) do { unsigned _sp = 0; while (cond) { __builtin_amdgcn_s_sleep(1); \
;     if ((++_sp & 255u) == 0u) { if (xb_ld(&(bar)[XB_TMO])) break; if (_sp > XB_SPIN_CAP) { atomicAdd(&(bar)[XB_TMO], 1u); break; } } } } while (0)
; __device__ __forceinline__ const float* in_ptr(int i) { return (const float*)gptr(i); }
; #define WSP() (gptr(22))
; __device__ __forceinline__ void xcd_barrier(const XcdBarrier& b) {
;     asm volatile("s_waitcnt vmcnt(0)" ::: "memory");
;     __syncthreads();
;     if (threadIdx.x == 0) {
;         unsigned* bar = b.bar;
;         __builtin_amdgcn_s_waitcnt(0);
;         unsigned nloc = b.st[0], nx = b.st[1];
;         if (nloc == 0u) { xcd_barrier_complete(bar, b.x, nloc, nx); b.st[0] = nloc; b.st[1] = nx; }
;         const unsigned old = xb_add(&bar[XB_XSUB(b.x)], 1u);
;         const unsigned gen = old / nloc;
;         if (old + 1u == (gen + 1u) * nloc) {
;             __builtin_amdgcn_fence(__ATOMIC_RELEASE, "agent");
;             asm volatile("s_waitcnt vmcnt(0)" ::: "memory");
;             const unsigned og = xb_add(&bar[XB_TOP], 1u);
;             const unsigned tg = og / nx;
;             if (og + 1u == (tg + 1u) * nx) xb_add(&bar[XB_TOPGEN], 1u);
;             else XB_SPIN(xb_ld(&bar[XB_TOPGEN]) == tg, bar);
;             __builtin_amdgcn_fence(__ATOMIC_ACQUIRE, "agent");
;             xb_add(&bar[XB_XGEN(b.x)], 1u);
;             asm volatile("s_waitcnt vmcnt(0)" ::: "memory");
;         } else {
;             XB_SPIN(xb_ld(&bar[XB_XGEN(b.x)]) == gen, bar);
;             __builtin_amdgcn_fence(__ATOMIC_ACQUIRE, "agent");
;             asm volatile("s_waitcnt vmcnt(0)" ::: "memory");
;         }
;     }
;     __syncthreads();
; }
; __global__ void __launch_bounds__(NTHREADS, 2) mega(Params P) {
;     ...
;         { unsigned char* ws = WSP(); ph_sgu_mix_fast((bf16*)(ws + WS_PROJ), (bf16*)(ws + WS_VLN), (bf16*)(ws + WS_WSG), in_ptr(I_SGU_B) + l * 512, (bf16*)(ws + WS_HB), (unsigned*)(ws + WS_CTL + CTL_QUEUE) + 64 * (4 + l)); }
;         GRID_BAR();
.LBB0_1725:
.LBB0_1751:
	v_mov_b32_e32 v1, 22
	s_barrier
	s_mov_b32 s2, s40
	v_lshl_add_u32 v1, v1, 3, 0
	v_add_u32_e32 v1, 0x23f10, v1
	ds_read_b64 v[4:5], v1
	s_waitcnt vmcnt(0)
	s_waitcnt lgkmcnt(0)
	s_barrier
	v_readfirstlane_b32 s5, v5
	v_readfirstlane_b32 s4, v4
	s_and_saveexec_b64 s[0:1], s[30:31]
	s_cbranch_execz .LBB0_1803
	v_readlane_b32 s3, v254, 36
	s_waitcnt vmcnt(0) expcnt(0) lgkmcnt(0)
	s_nop 0
	v_mov_b32_e32 v1, s3
	ds_read_b32 v4, v1
	v_readlane_b32 s3, v254, 37
	s_waitcnt lgkmcnt(0)
	v_cmp_ne_u32_e32 vcc, 0, v4
	v_mov_b32_e32 v1, s3
	ds_read_b32 v2, v1
	s_cbranch_vccnz .LBB0_1767
	v_readlane_b32 s6, v254, 0
	v_readlane_b32 s7, v254, 1
	s_load_dwordx2 s[10:11], s[6:7], 0x4
	s_add_u32 s6, s4, 0x1000
	s_addc_u32 s7, s5, 0
	s_add_u32 s8, s4, 0x1100
	s_addc_u32 s9, s5, 0
	s_waitcnt lgkmcnt(0)
	s_mul_i32 s3, s10, s33
	s_add_u32 s10, s4, 0x1200
	s_mul_i32 s3, s3, s11
	s_addc_u32 s11, s5, 0
	s_add_u32 s12, s4, 0x1300
	s_addc_u32 s13, s5, 0
	s_mov_b32 s20, 1
	s_branch .LBB0_1755

; __device__ __forceinline__ int ltid() { int t = threadIdx.x; asm volatile("" : "+v"(t)); return t; }
; __device__ __forceinline__ const float* in_ptr(int i) { return (const float*)gptr(i); }
; #define WSP() (gptr(22))
; __device__ __forceinline__ void ph_sgu_mix_fast(const bf16* __restrict__ proj, const bf16* __restrict__ VLN, const bf16* __restrict__ WSG, const float* __restrict__ sgu_b, bf16* __restrict__ mix, unsigned* __restrict__ queue) {
;     extern __shared__ __attribute__((aligned(16))) unsigned char lds_dyn[];
;     const int tid0 = ltid();
;     volatile unsigned* qw = (volatile unsigned*)(lds_dyn + 128 * SG_STR);
;     for (;;) {
;         int tid = tid0; asm volatile("" : "+v"(tid));
;         __syncthreads();
;         if (tid == 0) *qw = __hip_atomic_fetch_add(queue, 1u, __ATOMIC_RELAXED, __HIP_MEMORY_SCOPE_AGENT);
;         __syncthreads();
;         const int item = (int)*qw;
;         if (item >= BATCH * 32 * 4) break;
; __global__ void __launch_bounds__(NTHREADS, 2) mega(Params P) {
;     ...
;         { unsigned char* ws = WSP(); ph_sgu_mix_fast((bf16*)(ws + WS_PROJ), (bf16*)(ws + WS_VLN), (bf16*)(ws + WS_WSG), in_ptr(I_SGU_B) + l * 512, (bf16*)(ws + WS_HB), (unsigned*)(ws + WS_CTL + CTL_QUEUE) + 64 * (4 + l)); }
.LBB0_1869:
	v_mov_b32_e32 v1, 22
	s_waitcnt lgkmcnt(0)
	s_barrier
	v_readlane_b32 s0, v254, 35
	s_mov_b64 s[20:21], 0
	s_nop 0
	v_lshl_add_u32 v1, v1, 3, s0
	ds_read_b64 v[4:5], v1
	v_mov_b32_e32 v1, 10
	s_waitcnt lgkmcnt(0)
	v_readfirstlane_b32 s11, v5
	v_lshl_add_u32 v1, v1, 3, s0
	v_readfirstlane_b32 s10, v4
	ds_read_b64 v[4:5], v1
	s_add_u32 s12, s10, 0x3bc00000
	s_addc_u32 s13, s11, 0
	s_add_u32 s14, s10, 0x2df10000
	s_addc_u32 s15, s11, 0
	s_waitcnt lgkmcnt(0)
	v_readfirstlane_b32 s3, v4
	v_readlane_b32 s0, v255, 6
	s_mov_b32 s1, 0
	s_lshl_b32 s0, s0, 11
	v_readfirstlane_b32 s2, v5
	s_add_u32 s16, s3, s0
	s_addc_u32 s17, s2, s1
	v_readlane_b32 s0, v255, 8
	v_readlane_b32 s1, v255, 9
	s_add_u32 s0, s10, s0
	s_addc_u32 s1, s11, s1
	s_add_u32 s18, s0, 0x8400
	s_addc_u32 s19, s1, 0
	v_mov_b32_e32 v1, v0
	s_branch .LBB0_1728

; __device__ __forceinline__ void ph_sgu_mix_fast(const bf16* __restrict__ proj, const bf16* __restrict__ VLN, const bf16* __restrict__ WSG, const float* __restrict__ sgu_b, bf16* __restrict__ mix, unsigned* __restrict__ queue) {
;     ...
;         __syncthreads();
;         const int item = (int)*qw;
;         if (item >= BATCH * 32 * 4) break;
;         const int lane = tid & 63, wave = tid >> 6, r16 = lane & 15, a = lane >> 4;
;         const int g = item & 3, n = (item >> 2) & 31, b = item >> 7;
;         const size_t m0 = (size_t)b * SEQ + n * 128;
;         __syncthreads();
; #pragma unroll
;         for (int i = 0; i < 4; ++i) { const int c = tid + 512 * i, s = c >> 4, part = c & 15;
;             *(u32x4*)(lds_dyn + s * SG_STR + part * 16) = *(const u32x4*)(VLN + (m0 + s) * 512 + g * 128 + part * 8); }
;         const int nks = ((16 * wave + 15) >> 5) + 1;
;         bf16x8 wf[4];
; #pragma unroll
;         for (int ks = 0; ks < 4; ++ks) wf[ks] = ld_frag(WSG + ((size_t)g * 128 + 16 * wave + r16) * 128 + 32 * ks + 8 * a);
;         __syncthreads();
.LBB0_1732:
	s_or_b64 exec, exec, s[0:1]
	s_add_i32 s0, 0, 0x8800
	s_cmp_lg_u32 s0, -1
	s_cselect_b32 s0, s0, 0
	s_cselect_b32 s1, s25, 0
	v_mov_b32_e32 v4, s0
	v_mov_b32_e32 v5, s1
	s_waitcnt lgkmcnt(0)
	s_barrier
	flat_load_dword v28, v[4:5] sc0 sc1
	s_waitcnt vmcnt(0)
	s_mov_b64 s[0:1], -1
	s_waitcnt lgkmcnt(0)
	v_cmp_gt_i32_e32 vcc, 0x400, v28
	s_and_saveexec_b64 s[34:35], vcc
	s_cbranch_execz .LBB0_1727
	v_ashrrev_i32_e32 v4, 7, v28
	v_ashrrev_i32_e32 v5, 31, v4
	v_lshlrev_b64 v[24:25], 12, v[4:5]
	v_lshlrev_b32_e32 v2, 5, v28
	s_movk_i32 s0, 0xf80
	v_and_or_b32 v24, v2, s0, v24
	v_lshlrev_b32_e32 v2, 7, v28
	v_and_b32_e32 v2, 0x180, v2
	v_and_b32_e32 v27, 15, v26
	v_lshlrev_b32_e32 v6, 1, v2
	v_mov_b32_e32 v7, v3
	v_ashrrev_i32_e32 v14, 4, v26
	v_lshl_add_u64 v[6:7], s[12:13], 0, v[6:7]
	v_lshlrev_b32_e32 v22, 4, v27
	v_mov_b32_e32 v23, v3
	v_ashrrev_i32_e32 v15, 31, v14
	v_lshl_add_u64 v[10:11], v[6:7], 0, v[22:23]
	v_lshl_add_u64 v[6:7], v[24:25], 0, v[14:15]
	v_lshlrev_b64 v[6:7], 10, v[6:7]
	v_lshl_add_u64 v[6:7], v[10:11], 0, v[6:7]
	s_barrier
	global_load_dwordx4 v[6:9], v[6:7], off
	v_add_u32_e32 v12, 0, v22
	v_mad_u64_u32 v[14:15], s[0:1], v14, s93, v[12:13]
	v_ashrrev_i32_e32 v23, 2, v26
	v_bfe_u32 v29, v26, 4, 2
	v_bfi_b32 v30, -16, v23, v26
	v_ashrrev_i32_e32 v35, 7, v26
	v_mul_i32_i24_e32 v36, -14, v27
	v_ashrrev_i32_e32 v31, 31, v30
	s_movk_i32 s2, 0x880
	v_lshlrev_b64 v[4:5], 24, v[4:5]
	v_lshlrev_b32_e32 v34, 3, v29
	v_cmp_lt_i32_e64 s[4:5], 0, v35
	v_cmp_lt_i32_e64 s[6:7], 1, v35
	v_cmp_lt_i32_e64 s[8:9], 2, v35
	s_mov_b64 s[36:37], 0
	s_waitcnt vmcnt(0)
	ds_write_b128 v14, v[6:9]
	v_add_u32_e32 v6, 0x200, v26
	v_ashrrev_i32_e32 v14, 4, v6
	v_ashrrev_i32_e32 v15, 31, v14
	v_lshl_add_u64 v[6:7], v[24:25], 0, v[14:15]
	v_lshlrev_b64 v[6:7], 10, v[6:7]
	v_lshl_add_u64 v[6:7], v[10:11], 0, v[6:7]
	global_load_dwordx4 v[6:9], v[6:7], off
	v_mad_u64_u32 v[14:15], s[0:1], v14, s93, v[12:13]
	s_waitcnt vmcnt(0)
	ds_write_b128 v14, v[6:9]
	v_add_u32_e32 v6, 0x400, v26
	v_ashrrev_i32_e32 v14, 4, v6
	v_ashrrev_i32_e32 v15, 31, v14
	v_lshl_add_u64 v[6:7], v[24:25], 0, v[14:15]
	v_lshlrev_b64 v[6:7], 10, v[6:7]
	v_lshl_add_u64 v[6:7], v[10:11], 0, v[6:7]
	global_load_dwordx4 v[6:9], v[6:7], off
	v_mad_u64_u32 v[14:15], s[0:1], v14, s93, v[12:13]
	s_waitcnt vmcnt(0)
	ds_write_b128 v14, v[6:9]
	v_add_u32_e32 v6, 0x600, v26
	v_ashrrev_i32_e32 v14, 4, v6
	v_ashrrev_i32_e32 v15, 31, v14
	v_lshl_add_u64 v[6:7], v[24:25], 0, v[14:15]
	v_lshlrev_b64 v[6:7], 10, v[6:7]
	v_lshl_add_u64 v[6:7], v[10:11], 0, v[6:7]
	global_load_dwordx4 v[6:9], v[6:7], off
	v_mad_u64_u32 v[10:11], s[0:1], v14, s93, v[12:13]
	v_add_u32_e32 v26, v2, v30
	v_lshl_add_u64 v[24:25], v[24:25], 0, v[30:31]
	v_mad_u64_u32 v[32:33], s[0:1], v24, s23, 0
	v_cmp_lt_i32_e64 s[0:1], -1, v35
	s_waitcnt vmcnt(0)
	ds_write_b128 v10, v[6:9]
	v_and_b32_e32 v6, -16, v23
	v_ashrrev_i32_e32 v7, 31, v6
	v_lshl_add_u64 v[6:7], v[2:3], 0, v[6:7]
	v_or_b32_e32 v6, v6, v27
	v_lshlrev_b64 v[6:7], 8, v[6:7]
	v_lshl_add_u64 v[6:7], s[14:15], 0, v[6:7]
	v_lshlrev_b32_e32 v8, 4, v29
	v_mov_b32_e32 v9, v3
	v_lshl_add_u64 v[18:19], v[6:7], 0, v[8:9]
	v_ashrrev_i32_e32 v27, 31, v26
	global_load_dwordx4 v[6:9], v[18:19], off
	global_load_dwordx4 v[10:13], v[18:19], off offset:64
	global_load_dwordx4 v[14:17], v[18:19], off offset:128
	s_nop 0
	global_load_dwordx4 v[18:21], v[18:19], off offset:192
	v_lshl_add_u64 v[26:27], v[26:27], 2, s[16:17]
	s_waitcnt lgkmcnt(0)
	s_barrier
	global_load_dword v26, v[26:27], off
	v_mad_u32_u24 v2, v29, s2, v36
	v_add3_u32 v36, v2, v22, 0
	v_lshlrev_b32_e32 v2, 17, v28
	s_mov_b32 s2, 0xf80000
	v_mad_i32_i24 v23, v25, s23, v33
	v_and_or_b32 v4, v2, s2, v4
	v_lshlrev_b64 v[24:25], 12, v[30:31]
	v_lshlrev_b32_e32 v2, 8, v28
	v_lshl_add_u64 v[4:5], v[4:5], 0, v[24:25]
	v_and_b32_e32 v2, 0x300, v2
	v_or3_b32 v4, v4, v2, v34
	v_or3_b32 v22, v32, v2, v34
	v_lshl_add_u64 v[28:29], s[10:11], 0, v[4:5]
	v_lshl_add_u64 v[30:31], s[10:11], 0, v[22:23]
	s_waitcnt vmcnt(0)
	v_mov_b32_e32 v27, v26
	s_branch .LBB0_1735

; __device__ __forceinline__ void ph_sgu_mix_fast(const bf16* __restrict__ proj, const bf16* __restrict__ VLN, const bf16* __restrict__ WSG, const float* __restrict__ sgu_b, bf16* __restrict__ mix, unsigned* __restrict__ queue) {
;     ...
;     }
;     __syncthreads();
.Lsgu_exit:
	s_or_b64 exec, exec, s[20:21]
	v_readlane_b32 s30, v254, 60
	v_readlane_b32 s20, v255, 2
	s_lshl_b64 s[0:1], s[96:97], 26
	s_lshl_b64 s[4:5], s[96:97], 24
	v_readlane_b32 s31, v254, 61
	v_readlane_b32 s40, v254, 62
	v_readlane_b32 s75, v254, 63
	v_readlane_b32 s29, v255, 0
	v_readlane_b32 s41, v255, 1
	s_movk_i32 s50, 0x4100
	s_movk_i32 s51, 0xbff
	v_readlane_b32 s21, v255, 3
	s_barrier
	s_branch .LBB0_1873
